# ph3 epilogue q/u bf16 outputs also stored 16 bytes per lane (permlane16_swap pairing), on top of ph6/ph8 wide stores
# speedup vs baseline: 1.0191x; 1.0009x over previous
.LBB0_342:
	ds_read_b128 v[130:133], v182
	ds_read_b128 v[156:159], v182 offset:1024
	ds_read_b128 v[160:163], v182 offset:2048
	ds_read_b128 v[164:167], v182 offset:3072
	s_add_u32 s8, s6, 0xfff80080
	s_addc_u32 s9, s7, -1
	s_cmp_eq_u32 s39, 28
	s_cselect_b32 s11, s1, s9
	s_cselect_b32 s10, s3, s8
	s_cselect_b32 s9, s12, s38
	s_cselect_b32 s8, s13, s16
	v_lshl_add_u64 v[172:173], s[6:7], 0, v[148:149]
	s_add_i32 m0, s86, 0xc000
	ds_read_b128 v[168:171], v183
	ds_read_b128 v[190:193], v183 offset:1024
	ds_read_b128 v[194:197], v183 offset:2048
	ds_read_b128 v[198:201], v183 offset:3072
	ds_read_b128 v[202:205], v183 offset:4096
	ds_read_b128 v[206:209], v183 offset:5120
	ds_read_b128 v[210:213], v183 offset:6144
	ds_read_b128 v[214:217], v183 offset:7168
	global_load_lds_dwordx4 v[172:173], off
	v_lshl_add_u64 v[172:173], s[6:7], 0, v[150:151]
	s_add_i32 m0, s86, 0xe000
	s_nop 0
	global_load_lds_dwordx4 v[172:173], off
	s_waitcnt lgkmcnt(8)
	s_barrier
	s_waitcnt lgkmcnt(0)
	s_setprio 1
	s_waitcnt lgkmcnt(0)
	v_mfma_f32_16x16x32_bf16 v[126:129], v[130:133], v[168:171], v[126:129]
	v_mfma_f32_16x16x32_bf16 v[122:125], v[160:163], v[168:171], v[122:125]
	v_mfma_f32_16x16x32_bf16 v[110:113], v[130:133], v[194:197], v[110:113]
	v_mfma_f32_16x16x32_bf16 v[106:109], v[160:163], v[194:197], v[106:109]
	v_mfma_f32_16x16x32_bf16 v[94:97], v[130:133], v[202:205], v[94:97]
	v_mfma_f32_16x16x32_bf16 v[90:93], v[160:163], v[202:205], v[90:93]
	v_mfma_f32_16x16x32_bf16 v[78:81], v[130:133], v[210:213], v[78:81]
	v_mfma_f32_16x16x32_bf16 v[74:77], v[160:163], v[210:213], v[74:77]
	v_mfma_f32_16x16x32_bf16 v[126:129], v[156:159], v[190:193], v[126:129]
	v_mfma_f32_16x16x32_bf16 v[122:125], v[164:167], v[190:193], v[122:125]
	v_mfma_f32_16x16x32_bf16 v[110:113], v[156:159], v[198:201], v[110:113]
	v_mfma_f32_16x16x32_bf16 v[106:109], v[164:167], v[198:201], v[106:109]
	v_mfma_f32_16x16x32_bf16 v[94:97], v[156:159], v[206:209], v[94:97]
	v_mfma_f32_16x16x32_bf16 v[90:93], v[164:167], v[206:209], v[90:93]
	v_mfma_f32_16x16x32_bf16 v[78:81], v[156:159], v[214:217], v[78:81]
	v_mfma_f32_16x16x32_bf16 v[74:77], v[164:167], v[214:217], v[74:77]
	s_setprio 0
	s_barrier
	s_add_i32 s45, s31, s71
	v_lshl_add_u64 v[172:173], s[8:9], 0, v[134:135]
	s_mov_b32 m0, s45
	ds_read_b128 v[218:221], v184
	ds_read_b128 v[222:225], v184 offset:1024
	ds_read_b128 v[226:229], v184 offset:2048
	ds_read_b128 v[230:233], v184 offset:3072
	global_load_lds_dwordx4 v[172:173], off
	v_lshl_add_u64 v[234:235], s[8:9], 0, v[136:137]
	s_add_i32 m0, s45, 0x2000
	s_nop 0
	global_load_lds_dwordx4 v[234:235], off
	s_barrier
	s_waitcnt lgkmcnt(0)
	s_setprio 1
	s_waitcnt lgkmcnt(0)
	v_mfma_f32_16x16x32_bf16 v[118:121], v[218:221], v[168:171], v[118:121]
	v_mfma_f32_16x16x32_bf16 v[114:117], v[226:229], v[168:171], v[114:117]
	v_mfma_f32_16x16x32_bf16 v[102:105], v[218:221], v[194:197], v[102:105]
	v_mfma_f32_16x16x32_bf16 v[98:101], v[226:229], v[194:197], v[98:101]
	v_mfma_f32_16x16x32_bf16 v[86:89], v[218:221], v[202:205], v[86:89]
	v_mfma_f32_16x16x32_bf16 v[82:85], v[226:229], v[202:205], v[82:85]
	v_mfma_f32_16x16x32_bf16 v[70:73], v[218:221], v[210:213], v[70:73]
	v_mfma_f32_16x16x32_bf16 v[66:69], v[226:229], v[210:213], v[66:69]
	v_mfma_f32_16x16x32_bf16 v[118:121], v[222:225], v[190:193], v[118:121]
	v_mfma_f32_16x16x32_bf16 v[114:117], v[230:233], v[190:193], v[114:117]
	v_mfma_f32_16x16x32_bf16 v[102:105], v[222:225], v[198:201], v[102:105]
	v_mfma_f32_16x16x32_bf16 v[98:101], v[230:233], v[198:201], v[98:101]
	v_mfma_f32_16x16x32_bf16 v[86:89], v[222:225], v[206:209], v[86:89]
	v_mfma_f32_16x16x32_bf16 v[82:85], v[230:233], v[206:209], v[82:85]
	v_mfma_f32_16x16x32_bf16 v[70:73], v[222:225], v[214:217], v[70:73]
	v_mfma_f32_16x16x32_bf16 v[66:69], v[230:233], v[214:217], v[66:69]
	s_setprio 0
	s_mov_b32 m0, s86
	v_lshl_add_u64 v[236:237], s[10:11], 0, v[134:135]
	s_barrier
	ds_read_b128 v[168:171], v183 offset:16384
	ds_read_b128 v[190:193], v183 offset:17408
	ds_read_b128 v[194:197], v183 offset:18432
	ds_read_b128 v[198:201], v183 offset:19456
	ds_read_b128 v[202:205], v183 offset:20480
	ds_read_b128 v[206:209], v183 offset:21504
	ds_read_b128 v[210:213], v183 offset:22528
	ds_read_b128 v[214:217], v183 offset:23552
	global_load_lds_dwordx4 v[236:237], off
	v_lshl_add_u64 v[238:239], s[10:11], 0, v[136:137]
	s_mov_b32 m0, s87
	s_nop 0
	global_load_lds_dwordx4 v[238:239], off
	s_barrier
	s_waitcnt lgkmcnt(0)
	s_setprio 1
	s_waitcnt lgkmcnt(0)
	v_mfma_f32_16x16x32_bf16 v[62:65], v[130:133], v[168:171], v[62:65]
	v_mfma_f32_16x16x32_bf16 v[58:61], v[160:163], v[168:171], v[58:61]
	v_mfma_f32_16x16x32_bf16 v[46:49], v[130:133], v[194:197], v[46:49]
	v_mfma_f32_16x16x32_bf16 v[42:45], v[160:163], v[194:197], v[42:45]
	v_mfma_f32_16x16x32_bf16 v[30:33], v[130:133], v[202:205], v[30:33]
	v_mfma_f32_16x16x32_bf16 v[26:29], v[160:163], v[202:205], v[26:29]
	v_mfma_f32_16x16x32_bf16 v[14:17], v[130:133], v[210:213], v[14:17]
	v_mfma_f32_16x16x32_bf16 v[10:13], v[160:163], v[210:213], v[10:13]
	v_mfma_f32_16x16x32_bf16 v[62:65], v[156:159], v[190:193], v[62:65]
	v_mfma_f32_16x16x32_bf16 v[58:61], v[164:167], v[190:193], v[58:61]
	v_mfma_f32_16x16x32_bf16 v[46:49], v[156:159], v[198:201], v[46:49]
	v_mfma_f32_16x16x32_bf16 v[42:45], v[164:167], v[198:201], v[42:45]
	v_mfma_f32_16x16x32_bf16 v[30:33], v[156:159], v[206:209], v[30:33]
	v_mfma_f32_16x16x32_bf16 v[26:29], v[164:167], v[206:209], v[26:29]
	v_mfma_f32_16x16x32_bf16 v[14:17], v[156:159], v[214:217], v[14:17]
	v_mfma_f32_16x16x32_bf16 v[10:13], v[164:167], v[214:217], v[10:13]
	s_setprio 0
	s_barrier
	s_add_u32 s52, s8, 0x80000
	s_addc_u32 s53, s9, 0
	s_add_i32 s45, s36, s71
	v_lshl_add_u64 v[130:131], s[52:53], 0, v[134:135]
	s_mov_b32 m0, s45
	s_nop 0
	global_load_lds_dwordx4 v[130:131], off
	v_lshl_add_u64 v[130:131], s[52:53], 0, v[136:137]
	s_add_i32 m0, s45, 0x2000
	s_nop 0
	global_load_lds_dwordx4 v[130:131], off
	s_waitcnt vmcnt(6)
	s_barrier
	s_setprio 1
	v_mfma_f32_16x16x32_bf16 v[54:57], v[218:221], v[168:171], v[54:57]
	v_mfma_f32_16x16x32_bf16 v[50:53], v[226:229], v[168:171], v[50:53]
	v_mfma_f32_16x16x32_bf16 v[38:41], v[218:221], v[194:197], v[38:41]
	v_mfma_f32_16x16x32_bf16 v[34:37], v[226:229], v[194:197], v[34:37]
	v_mfma_f32_16x16x32_bf16 v[22:25], v[218:221], v[202:205], v[22:25]
	v_mfma_f32_16x16x32_bf16 v[18:21], v[226:229], v[202:205], v[18:21]
	v_mfma_f32_16x16x32_bf16 v[6:9], v[218:221], v[210:213], v[6:9]
	v_mfma_f32_16x16x32_bf16 v[2:5], v[226:229], v[210:213], v[2:5]
	v_mfma_f32_16x16x32_bf16 v[54:57], v[222:225], v[190:193], v[54:57]
	v_mfma_f32_16x16x32_bf16 v[50:53], v[230:233], v[190:193], v[50:53]
	v_mfma_f32_16x16x32_bf16 v[38:41], v[222:225], v[198:201], v[38:41]
	v_mfma_f32_16x16x32_bf16 v[34:37], v[230:233], v[198:201], v[34:37]
	v_mfma_f32_16x16x32_bf16 v[22:25], v[222:225], v[206:209], v[22:25]
	v_mfma_f32_16x16x32_bf16 v[18:21], v[230:233], v[206:209], v[18:21]
	v_mfma_f32_16x16x32_bf16 v[6:9], v[222:225], v[214:217], v[6:9]
	v_mfma_f32_16x16x32_bf16 v[2:5], v[230:233], v[214:217], v[2:5]
	s_setprio 0
	s_add_i32 s45, 0, 0x18000
	v_add_u32_e32 v138, s45, v141
	s_barrier
	ds_read_b128 v[130:133], v138
	ds_read_b128 v[156:159], v138 offset:1024
	ds_read_b128 v[160:163], v138 offset:2048
	ds_read_b128 v[164:167], v138 offset:3072
	s_add_u32 s10, s10, 0x80000
	s_addc_u32 s11, s11, 0
	s_mov_b32 m0, s96
	v_lshl_add_u64 v[218:219], s[10:11], 0, v[134:135]
	ds_read_b128 v[168:171], v183 offset:32768
	ds_read_b128 v[190:193], v183 offset:33792
	ds_read_b128 v[194:197], v183 offset:34816
	ds_read_b128 v[198:201], v183 offset:35840
	ds_read_b128 v[202:205], v183 offset:36864
	ds_read_b128 v[206:209], v183 offset:37888
	ds_read_b128 v[210:213], v183 offset:38912
	ds_read_b128 v[214:217], v183 offset:39936
	global_load_lds_dwordx4 v[218:219], off
	v_lshl_add_u64 v[218:219], s[10:11], 0, v[136:137]
	s_mov_b32 m0, s97
	s_nop 0
	global_load_lds_dwordx4 v[218:219], off
	s_waitcnt lgkmcnt(8)
	s_barrier
	s_waitcnt lgkmcnt(0)
	s_setprio 1
	s_waitcnt lgkmcnt(0)
	v_mfma_f32_16x16x32_bf16 v[126:129], v[130:133], v[168:171], v[126:129]
	v_mfma_f32_16x16x32_bf16 v[122:125], v[160:163], v[168:171], v[122:125]
	v_mfma_f32_16x16x32_bf16 v[110:113], v[130:133], v[194:197], v[110:113]
	v_mfma_f32_16x16x32_bf16 v[106:109], v[160:163], v[194:197], v[106:109]
	v_mfma_f32_16x16x32_bf16 v[94:97], v[130:133], v[202:205], v[94:97]
	v_mfma_f32_16x16x32_bf16 v[90:93], v[160:163], v[202:205], v[90:93]
	v_mfma_f32_16x16x32_bf16 v[78:81], v[130:133], v[210:213], v[78:81]
	v_mfma_f32_16x16x32_bf16 v[74:77], v[160:163], v[210:213], v[74:77]
	v_mfma_f32_16x16x32_bf16 v[126:129], v[156:159], v[190:193], v[126:129]
	v_mfma_f32_16x16x32_bf16 v[122:125], v[164:167], v[190:193], v[122:125]
	v_mfma_f32_16x16x32_bf16 v[110:113], v[156:159], v[198:201], v[110:113]
	v_mfma_f32_16x16x32_bf16 v[106:109], v[164:167], v[198:201], v[106:109]
	v_mfma_f32_16x16x32_bf16 v[94:97], v[156:159], v[206:209], v[94:97]
	v_mfma_f32_16x16x32_bf16 v[90:93], v[164:167], v[206:209], v[90:93]
	v_mfma_f32_16x16x32_bf16 v[78:81], v[156:159], v[214:217], v[78:81]
	v_mfma_f32_16x16x32_bf16 v[74:77], v[164:167], v[214:217], v[74:77]
	s_setprio 0
	s_barrier
	s_add_i32 s10, 0, 0x1c000
	s_add_i32 s11, s45, s71
	v_add_u32_e32 v138, s10, v141
	v_lshl_add_u64 v[172:173], v[172:173], 0, s[26:27]
	s_mov_b32 m0, s11
	ds_read_b128 v[218:221], v138
	ds_read_b128 v[222:225], v138 offset:1024
	ds_read_b128 v[226:229], v138 offset:2048
	ds_read_b128 v[230:233], v138 offset:3072
	global_load_lds_dwordx4 v[172:173], off
	v_lshl_add_u64 v[172:173], v[234:235], 0, s[26:27]
	s_add_i32 m0, s11, 0x2000
	s_nop 0
	global_load_lds_dwordx4 v[172:173], off
	s_barrier
	s_waitcnt lgkmcnt(0)
	s_setprio 1
	s_waitcnt lgkmcnt(0)
	v_mfma_f32_16x16x32_bf16 v[118:121], v[218:221], v[168:171], v[118:121]
	v_mfma_f32_16x16x32_bf16 v[114:117], v[226:229], v[168:171], v[114:117]
	v_mfma_f32_16x16x32_bf16 v[102:105], v[218:221], v[194:197], v[102:105]
	v_mfma_f32_16x16x32_bf16 v[98:101], v[226:229], v[194:197], v[98:101]
	v_mfma_f32_16x16x32_bf16 v[86:89], v[218:221], v[202:205], v[86:89]
	v_mfma_f32_16x16x32_bf16 v[82:85], v[226:229], v[202:205], v[82:85]
	v_mfma_f32_16x16x32_bf16 v[70:73], v[218:221], v[210:213], v[70:73]
	v_mfma_f32_16x16x32_bf16 v[66:69], v[226:229], v[210:213], v[66:69]
	v_mfma_f32_16x16x32_bf16 v[118:121], v[222:225], v[190:193], v[118:121]
	v_mfma_f32_16x16x32_bf16 v[114:117], v[230:233], v[190:193], v[114:117]
	v_mfma_f32_16x16x32_bf16 v[102:105], v[222:225], v[198:201], v[102:105]
	v_mfma_f32_16x16x32_bf16 v[98:101], v[230:233], v[198:201], v[98:101]
	v_mfma_f32_16x16x32_bf16 v[86:89], v[222:225], v[206:209], v[86:89]
	v_mfma_f32_16x16x32_bf16 v[82:85], v[230:233], v[206:209], v[82:85]
	v_mfma_f32_16x16x32_bf16 v[70:73], v[222:225], v[214:217], v[70:73]
	v_mfma_f32_16x16x32_bf16 v[66:69], v[230:233], v[214:217], v[66:69]
	s_setprio 0
	s_mov_b32 m0, s14
	v_lshl_add_u64 v[172:173], v[236:237], 0, s[26:27]
	s_barrier
	ds_read_b128 v[168:171], v183 offset:49152
	ds_read_b128 v[190:193], v183 offset:50176
	ds_read_b128 v[194:197], v183 offset:51200
	ds_read_b128 v[198:201], v183 offset:52224
	ds_read_b128 v[202:205], v183 offset:53248
	ds_read_b128 v[206:209], v183 offset:54272
	ds_read_b128 v[210:213], v183 offset:55296
	ds_read_b128 v[214:217], v183 offset:56320
	global_load_lds_dwordx4 v[172:173], off
	v_lshl_add_u64 v[172:173], v[238:239], 0, s[26:27]
	s_mov_b32 m0, s15
	s_nop 0
	global_load_lds_dwordx4 v[172:173], off
	s_barrier
	s_waitcnt lgkmcnt(0)
	s_setprio 1
	s_waitcnt lgkmcnt(0)
	v_mfma_f32_16x16x32_bf16 v[62:65], v[130:133], v[168:171], v[62:65]
	v_mfma_f32_16x16x32_bf16 v[58:61], v[160:163], v[168:171], v[58:61]
	v_mfma_f32_16x16x32_bf16 v[46:49], v[130:133], v[194:197], v[46:49]
	v_mfma_f32_16x16x32_bf16 v[42:45], v[160:163], v[194:197], v[42:45]
	v_mfma_f32_16x16x32_bf16 v[30:33], v[130:133], v[202:205], v[30:33]
	v_mfma_f32_16x16x32_bf16 v[26:29], v[160:163], v[202:205], v[26:29]
	v_mfma_f32_16x16x32_bf16 v[14:17], v[130:133], v[210:213], v[14:17]
	v_mfma_f32_16x16x32_bf16 v[10:13], v[160:163], v[210:213], v[10:13]
	v_mfma_f32_16x16x32_bf16 v[62:65], v[156:159], v[190:193], v[62:65]
	v_mfma_f32_16x16x32_bf16 v[58:61], v[164:167], v[190:193], v[58:61]
	v_mfma_f32_16x16x32_bf16 v[46:49], v[156:159], v[198:201], v[46:49]
	v_mfma_f32_16x16x32_bf16 v[42:45], v[164:167], v[198:201], v[42:45]
	v_mfma_f32_16x16x32_bf16 v[30:33], v[156:159], v[206:209], v[30:33]
	v_mfma_f32_16x16x32_bf16 v[26:29], v[164:167], v[206:209], v[26:29]
	v_mfma_f32_16x16x32_bf16 v[14:17], v[156:159], v[214:217], v[14:17]
	v_mfma_f32_16x16x32_bf16 v[10:13], v[164:167], v[214:217], v[10:13]
	s_setprio 0
	s_barrier
	s_add_u32 s8, s8, 0x80080
	s_addc_u32 s9, s9, 0
	s_add_i32 s10, s10, s71
	v_lshl_add_u64 v[130:131], s[8:9], 0, v[134:135]
	s_mov_b32 m0, s10
	s_nop 0
	global_load_lds_dwordx4 v[130:131], off
	v_lshl_add_u64 v[130:131], s[8:9], 0, v[136:137]
	s_add_i32 m0, s10, 0x2000
	s_nop 0
	global_load_lds_dwordx4 v[130:131], off
	s_waitcnt vmcnt(6)
	s_barrier
	s_setprio 1
	v_mfma_f32_16x16x32_bf16 v[54:57], v[218:221], v[168:171], v[54:57]
	v_mfma_f32_16x16x32_bf16 v[50:53], v[226:229], v[168:171], v[50:53]
	v_mfma_f32_16x16x32_bf16 v[38:41], v[218:221], v[194:197], v[38:41]
	v_mfma_f32_16x16x32_bf16 v[34:37], v[226:229], v[194:197], v[34:37]
	v_mfma_f32_16x16x32_bf16 v[22:25], v[218:221], v[202:205], v[22:25]
	v_mfma_f32_16x16x32_bf16 v[18:21], v[226:229], v[202:205], v[18:21]
	v_mfma_f32_16x16x32_bf16 v[6:9], v[218:221], v[210:213], v[6:9]
	v_mfma_f32_16x16x32_bf16 v[2:5], v[226:229], v[210:213], v[2:5]
	v_mfma_f32_16x16x32_bf16 v[54:57], v[222:225], v[190:193], v[54:57]
	v_mfma_f32_16x16x32_bf16 v[50:53], v[230:233], v[190:193], v[50:53]
	v_mfma_f32_16x16x32_bf16 v[38:41], v[222:225], v[198:201], v[38:41]
	v_mfma_f32_16x16x32_bf16 v[34:37], v[230:233], v[198:201], v[34:37]
	v_mfma_f32_16x16x32_bf16 v[22:25], v[222:225], v[206:209], v[22:25]
	v_mfma_f32_16x16x32_bf16 v[18:21], v[230:233], v[206:209], v[18:21]
	v_mfma_f32_16x16x32_bf16 v[6:9], v[222:225], v[214:217], v[6:9]
	v_mfma_f32_16x16x32_bf16 v[2:5], v[230:233], v[214:217], v[2:5]
	s_setprio 0
	s_add_i32 s39, s39, 2
	s_add_u32 s6, s6, 0x100
	s_addc_u32 s7, s7, 0
	s_add_u32 s16, s16, 0x100
	s_addc_u32 s38, s38, 0
	s_cmp_gt_u32 s39, 29
	s_barrier
	s_cbranch_scc0 .LBB0_342
	v_bfe_u32 v224, v185, 4, 1
	v_mov_b32_e32 v225, 0
	v_mul_u32_u24_e32 v224, 24, v224
	s_add_i32 s62, s2, -4
	s_and_b32 s63, s2, 1
	s_lshr_b32 s64, s62, 1
	s_cmp_eq_u32 s63, 0
	s_cselect_b64 s[12:13], -1, 0
	s_cmp_gt_i32 s62, 1
	s_cselect_b64 s[62:63], -1, 0
	s_and_b64 s[12:13], s[12:13], s[62:63]
	s_cmp_lt_u32 s64, 3
	s_cselect_b64 s[62:63], -1, 0
	s_lshl_b32 s64, s64, 6
	s_and_b64 s[12:13], s[12:13], s[62:63]
	s_mov_b32 s65, 0
	v_lshl_add_u64 v[196:197], s[64:65], 2, v[144:145]
	v_cndmask_b32_e64 v196, v146, v196, s[12:13]
	v_cndmask_b32_e64 v197, v147, v197, s[12:13]
	global_load_dwordx4 v[200:203], v[196:197], off
	global_load_dwordx4 v[204:207], v[196:197], off offset:64
	global_load_dwordx4 v[208:211], v[196:197], off offset:128
	global_load_dwordx4 v[212:215], v[196:197], off offset:192
	v_and_b32_e32 v131, 64, v185
	v_xor_b32_e32 v130, 16, v185
	v_add_u32_e32 v131, 64, v131
	v_cmp_lt_i32_e32 vcc, v130, v131
	s_cmp_gt_i32 s0, 63
	s_cselect_b64 s[6:7], -1, 0
	v_cndmask_b32_e32 v130, v185, v130, vcc
	v_lshlrev_b32_e32 v189, 2, v130
	v_xor_b32_e32 v130, 32, v185
	v_cmp_lt_i32_e32 vcc, v130, v131
	s_cmp_lt_i32 s0, 64
	s_cselect_b64 s[52:53], -1, 0
	v_cndmask_b32_e32 v130, v185, v130, vcc
	v_lshlrev_b32_e32 v190, 2, v130
	v_mul_f32_e32 v130, v127, v127
	v_fmac_f32_e32 v130, v126, v126
	v_fmac_f32_e32 v130, v128, v128
	v_fmac_f32_e32 v130, v129, v129
	v_fmac_f32_e32 v130, v122, v122
	v_fmac_f32_e32 v130, v123, v123
	v_fmac_f32_e32 v130, v124, v124
	v_fmac_f32_e32 v130, v125, v125
	v_fmac_f32_e32 v130, v118, v118
	v_fmac_f32_e32 v130, v119, v119
	v_fmac_f32_e32 v130, v120, v120
	v_fmac_f32_e32 v130, v121, v121
	v_fmac_f32_e32 v130, v114, v114
	v_fmac_f32_e32 v130, v115, v115
	v_fmac_f32_e32 v130, v116, v116
	v_fmac_f32_e32 v130, v117, v117
	ds_bpermute_b32 v131, v189, v130
	s_cmp_gt_i32 s2, 3
	s_cselect_b64 s[10:11], -1, 0
	s_cmp_gt_u32 s2, 9
	s_cselect_b64 s[12:13], -1, 0
	s_waitcnt lgkmcnt(0)
	v_add_f32_e32 v130, v130, v131
	s_cmp_lg_u32 s2, 10
	ds_bpermute_b32 v131, v190, v130
	s_cselect_b64 s[60:61], -1, 0
	s_add_i32 s1, s2, -4
	s_lshl_b32 s39, s2, 8
	s_lshr_b32 s8, s1, 1
	s_and_b32 s9, s2, 1
	s_cmp_eq_u32 s9, 0
	s_cselect_b64 s[2:3], -1, 0
	s_cmp_gt_u32 s1, 1
	s_cselect_b64 s[54:55], -1, 0
	s_lshl_b32 s1, s9, 8
	s_waitcnt lgkmcnt(0)
	v_add_f32_e32 v130, v130, v131
	s_and_b64 s[58:59], s[2:3], s[54:55]
	s_or_b32 s45, s1, s34
	s_lshl_b32 s16, s8, 6
	v_fmamk_f32 v130, v130, 0x3c800000, v188
	s_cmp_lg_u32 s8, 1
	v_rsq_f32_e32 v158, v130
	s_cselect_b64 s[56:57], -1, 0
	s_lshl_b32 s47, s0, 8
	v_readlane_b32 s0, v253, 42
	s_add_i32 s47, s47, s0
	v_add_u32_e32 v138, s39, v175
	v_or_b32_e32 v156, s47, v1
	s_ashr_i32 s38, s47, 11
	s_mov_b64 s[0:1], -1
	s_waitcnt vmcnt(0)
	s_and_b64 vcc, exec, s[10:11]
	s_cbranch_vccz .LBB0_429
	v_add_u32_e32 v164, 0xffffc000, v156
	v_and_b32_e32 v131, 0x7cf, v156
	v_ashrrev_i32_e32 v130, 3, v164
	v_cndmask_b32_e64 v165, v131, v174, s[6:7]
	v_mov_b32_e32 v131, s38
	v_cndmask_b32_e64 v162, v131, v130, s[6:7]
	s_and_b64 vcc, exec, s[12:13]
	s_cbranch_vccz .LBB0_359
	s_andn2_b64 vcc, exec, s[60:61]
	s_cbranch_vccnz .LBB0_355
	v_add_u32_e32 v132, 7, v165
	v_mov_b32_e32 v133, v139
	v_mad_i64_i32 v[132:133], s[0:1], v162, 15, v[132:133]
	v_ashrrev_i32_e32 v157, 31, v156
	v_readlane_b32 s0, v253, 43
	v_lshlrev_b64 v[130:131], 11, v[156:157]
	v_lshlrev_b64 v[132:133], 12, v[132:133]
	v_readlane_b32 s1, v253, 44
	v_lshl_add_u64 v[130:131], s[24:25], 0, v[130:131]
	v_lshl_add_u64 v[130:131], v[138:139], 1, v[130:131]
	v_lshl_add_u64 v[132:133], s[0:1], 0, v[132:133]
	v_cvt_pk_bf16_f32 v216, v126, v127
	v_cvt_pk_bf16_f32 v217, v128, v129
	s_and_b64 vcc, exec, s[6:7]
	v_lshl_add_u64 v[132:133], v[138:139], 2, v[132:133]
	s_cbranch_vccz .LBB0_348
	global_store_dwordx4 v[132:133], v[126:129], off
.LBB0_348:
	v_cndmask_b32_e64 v157, 0, 1, s[6:7]
	v_cvt_pk_bf16_f32 v218, v122, v123
	v_cvt_pk_bf16_f32 v219, v124, v125
	v_cmp_ne_u32_e64 s[0:1], 1, v157
	s_andn2_b64 vcc, exec, s[6:7]
	s_nop 1
	v_permlane16_swap_b32_e32 v216, v218
	v_permlane16_swap_b32_e32 v217, v219
	v_lshl_add_u64 v[226:227], v[224:225], 0, v[130:131]
	global_store_dwordx4 v[226:227], v[216:219], off
	s_cbranch_vccnz .LBB0_350
	global_store_dwordx4 v[132:133], v[122:125], off offset:64
.LBB0_350:
	v_cvt_pk_bf16_f32 v220, v118, v119
	v_cvt_pk_bf16_f32 v221, v120, v121
	s_and_b64 vcc, exec, s[0:1]
	s_cbranch_vccnz .LBB0_352
	global_store_dwordx4 v[132:133], v[118:121], off offset:128
.LBB0_352:
	v_cvt_pk_bf16_f32 v222, v114, v115
	v_cvt_pk_bf16_f32 v223, v116, v117
	s_and_b64 vcc, exec, s[0:1]
	s_nop 1
	v_permlane16_swap_b32_e32 v220, v222
	v_permlane16_swap_b32_e32 v221, v223
	global_store_dwordx4 v[226:227], v[220:223], off offset:64
	s_cbranch_vccnz .LBB0_354
	global_store_dwordx4 v[132:133], v[114:117], off offset:192

.LBB0_429:
	s_or_b32 s62, s39, s34
	s_ashr_i32 s63, s62, 31
	s_andn2_b64 vcc, exec, s[0:1]
	v_lshlrev_b32_e32 v130, 1, v140
	s_cbranch_vccnz .LBB0_431
	v_ashrrev_i32_e32 v157, 31, v156
	v_lshlrev_b64 v[132:133], 11, v[156:157]
	v_mul_f32_e32 v156, 0x3e38aa3b, v158
	v_pk_mul_f32 v[158:159], v[128:129], v[156:157] op_sel_hi:[1,0]
	v_pk_mul_f32 v[160:161], v[126:127], v[156:157] op_sel_hi:[1,0]
	v_lshl_add_u64 v[132:133], s[18:19], 0, v[132:133]
	v_lshl_add_u64 v[132:133], s[62:63], 1, v[132:133]
	v_mov_b32_e32 v131, v139
	v_lshl_add_u64 v[132:133], v[132:133], 0, v[130:131]
	v_pk_mul_f32 v[128:129], v[158:159], v[202:203]
	v_pk_mul_f32 v[126:127], v[160:161], v[200:201]
	s_nop 0
	v_cvt_pk_bf16_f32 v216, v126, v127
	v_cvt_pk_bf16_f32 v217, v128, v129
	v_pk_mul_f32 v[126:127], v[124:125], v[156:157] op_sel_hi:[1,0]
	v_pk_mul_f32 v[128:129], v[122:123], v[156:157] op_sel_hi:[1,0]
	v_pk_mul_f32 v[124:125], v[126:127], v[206:207]
	v_pk_mul_f32 v[122:123], v[128:129], v[204:205]
	s_nop 0
	v_cvt_pk_bf16_f32 v218, v122, v123
	v_cvt_pk_bf16_f32 v219, v124, v125
	s_nop 1
	v_permlane16_swap_b32_e32 v216, v218
	v_permlane16_swap_b32_e32 v217, v219
	v_lshl_add_u64 v[226:227], v[224:225], 0, v[132:133]
	global_store_dwordx4 v[226:227], v[216:219], off
	v_pk_mul_f32 v[122:123], v[120:121], v[156:157] op_sel_hi:[1,0]
	v_pk_mul_f32 v[124:125], v[118:119], v[156:157] op_sel_hi:[1,0]
	v_pk_mul_f32 v[120:121], v[122:123], v[210:211]
	v_pk_mul_f32 v[118:119], v[124:125], v[208:209]
	s_nop 0
	v_cvt_pk_bf16_f32 v220, v118, v119
	v_cvt_pk_bf16_f32 v221, v120, v121
	v_pk_mul_f32 v[118:119], v[116:117], v[156:157] op_sel_hi:[1,0]
	v_pk_mul_f32 v[120:121], v[114:115], v[156:157] op_sel_hi:[1,0]
	v_pk_mul_f32 v[116:117], v[118:119], v[214:215]
	v_pk_mul_f32 v[114:115], v[120:121], v[212:213]
	s_nop 0
	v_cvt_pk_bf16_f32 v222, v114, v115
	v_cvt_pk_bf16_f32 v223, v116, v117
	s_nop 1
	v_permlane16_swap_b32_e32 v220, v222
	v_permlane16_swap_b32_e32 v221, v223
	global_store_dwordx4 v[226:227], v[220:223], off offset:64
.LBB0_431:
	v_mul_f32_e32 v114, v111, v111
	v_fmac_f32_e32 v114, v110, v110
	v_fmac_f32_e32 v114, v112, v112
	v_fmac_f32_e32 v114, v113, v113
	v_fmac_f32_e32 v114, v106, v106
	v_fmac_f32_e32 v114, v107, v107
	v_fmac_f32_e32 v114, v108, v108
	v_fmac_f32_e32 v114, v109, v109
	v_fmac_f32_e32 v114, v102, v102
	v_fmac_f32_e32 v114, v103, v103
	v_fmac_f32_e32 v114, v104, v104
	v_fmac_f32_e32 v114, v105, v105
	v_fmac_f32_e32 v114, v98, v98
	v_fmac_f32_e32 v114, v99, v99
	v_fmac_f32_e32 v114, v100, v100
	v_fmac_f32_e32 v114, v101, v101
	ds_bpermute_b32 v115, v189, v114
	v_or_b32_e32 v118, s47, v179
	s_mov_b64 s[8:9], -1
	s_andn2_b64 vcc, exec, s[10:11]
	s_waitcnt lgkmcnt(0)
	v_add_f32_e32 v114, v114, v115
	ds_bpermute_b32 v115, v190, v114
	s_waitcnt lgkmcnt(0)
	v_add_f32_e32 v114, v114, v115
	v_fmamk_f32 v114, v114, 0x3c800000, v188
	v_rsq_f32_e32 v120, v114
	v_cndmask_b32_e64 v114, 0, 1, s[10:11]
	v_cmp_ne_u32_e64 s[2:3], 1, v114
	v_cndmask_b32_e64 v114, 0, 1, s[12:13]
	v_cmp_ne_u32_e64 s[0:1], 1, v114
	s_cbranch_vccnz .LBB0_517
	v_add_u32_e32 v126, 0xffffc000, v118
	v_and_b32_e32 v115, 0x7df, v118
	v_ashrrev_i32_e32 v114, 3, v126
	v_cndmask_b32_e64 v127, v115, v174, s[6:7]
	v_mov_b32_e32 v115, s38
	v_cndmask_b32_e64 v124, v115, v114, s[6:7]
	s_and_b64 vcc, exec, s[0:1]
	s_cbranch_vccnz .LBB0_447
	s_andn2_b64 vcc, exec, s[60:61]
	s_cbranch_vccnz .LBB0_443
	v_add_u32_e32 v116, 7, v127
	v_mov_b32_e32 v117, v139
	v_ashrrev_i32_e32 v119, 31, v118
	v_mad_i64_i32 v[116:117], s[8:9], v124, 15, v[116:117]
	v_readlane_b32 s10, v253, 43
	v_lshlrev_b64 v[114:115], 11, v[118:119]
	v_lshlrev_b64 v[116:117], 12, v[116:117]
	v_readlane_b32 s11, v253, 44
	v_lshl_add_u64 v[114:115], s[24:25], 0, v[114:115]
	v_cndmask_b32_e64 v119, 0, 1, s[6:7]
	v_lshl_add_u64 v[116:117], s[10:11], 0, v[116:117]
	v_lshl_add_u64 v[114:115], v[138:139], 1, v[114:115]
	v_cvt_pk_bf16_f32 v216, v110, v111
	v_cvt_pk_bf16_f32 v217, v112, v113
	v_cmp_ne_u32_e64 s[8:9], 1, v119
	s_andn2_b64 vcc, exec, s[6:7]
	v_lshl_add_u64 v[116:117], v[138:139], 2, v[116:117]
	s_cbranch_vccnz .LBB0_436
	global_store_dwordx4 v[116:117], v[110:113], off
.LBB0_436:
	v_cvt_pk_bf16_f32 v218, v106, v107
	v_cvt_pk_bf16_f32 v219, v108, v109
	s_and_b64 vcc, exec, s[8:9]
	s_nop 1
	v_permlane16_swap_b32_e32 v216, v218
	v_permlane16_swap_b32_e32 v217, v219
	v_lshl_add_u64 v[226:227], v[224:225], 0, v[114:115]
	global_store_dwordx4 v[226:227], v[216:219], off
	s_cbranch_vccnz .LBB0_438
	global_store_dwordx4 v[116:117], v[106:109], off offset:64
.LBB0_438:
	v_cvt_pk_bf16_f32 v220, v102, v103
	v_cvt_pk_bf16_f32 v221, v104, v105
	s_and_b64 vcc, exec, s[8:9]
	s_cbranch_vccnz .LBB0_440
	global_store_dwordx4 v[116:117], v[102:105], off offset:128
.LBB0_440:
	v_cvt_pk_bf16_f32 v222, v98, v99
	v_cvt_pk_bf16_f32 v223, v100, v101
	s_and_b64 vcc, exec, s[8:9]
	s_nop 1
	v_permlane16_swap_b32_e32 v220, v222
	v_permlane16_swap_b32_e32 v221, v223
	global_store_dwordx4 v[226:227], v[220:223], off offset:64
	s_cbranch_vccnz .LBB0_442
	global_store_dwordx4 v[116:117], v[98:101], off offset:192

.LBB0_517:
	s_andn2_b64 vcc, exec, s[8:9]
	s_cbranch_vccnz .LBB0_519
	v_ashrrev_i32_e32 v119, 31, v118
	v_mul_f32_e32 v116, 0x3e38aa3b, v120
	v_lshlrev_b64 v[114:115], 11, v[118:119]
	v_pk_mul_f32 v[118:119], v[112:113], v[116:117] op_sel_hi:[1,0]
	v_pk_mul_f32 v[120:121], v[110:111], v[116:117] op_sel_hi:[1,0]
	v_lshl_add_u64 v[114:115], s[18:19], 0, v[114:115]
	v_lshl_add_u64 v[114:115], s[62:63], 1, v[114:115]
	v_mov_b32_e32 v131, v139
	v_lshl_add_u64 v[114:115], v[114:115], 0, v[130:131]
	v_pk_mul_f32 v[112:113], v[118:119], v[202:203]
	v_pk_mul_f32 v[110:111], v[120:121], v[200:201]
	s_nop 0
	v_cvt_pk_bf16_f32 v216, v110, v111
	v_cvt_pk_bf16_f32 v217, v112, v113
	v_pk_mul_f32 v[110:111], v[108:109], v[116:117] op_sel_hi:[1,0]
	v_pk_mul_f32 v[112:113], v[106:107], v[116:117] op_sel_hi:[1,0]
	v_pk_mul_f32 v[108:109], v[110:111], v[206:207]
	v_pk_mul_f32 v[106:107], v[112:113], v[204:205]
	s_nop 0
	v_cvt_pk_bf16_f32 v218, v106, v107
	v_cvt_pk_bf16_f32 v219, v108, v109
	s_nop 1
	v_permlane16_swap_b32_e32 v216, v218
	v_permlane16_swap_b32_e32 v217, v219
	v_lshl_add_u64 v[226:227], v[224:225], 0, v[114:115]
	global_store_dwordx4 v[226:227], v[216:219], off
	v_pk_mul_f32 v[106:107], v[104:105], v[116:117] op_sel_hi:[1,0]
	v_pk_mul_f32 v[108:109], v[102:103], v[116:117] op_sel_hi:[1,0]
	v_pk_mul_f32 v[104:105], v[106:107], v[210:211]
	v_pk_mul_f32 v[102:103], v[108:109], v[208:209]
	s_nop 0
	v_cvt_pk_bf16_f32 v220, v102, v103
	v_cvt_pk_bf16_f32 v221, v104, v105
	v_pk_mul_f32 v[102:103], v[100:101], v[116:117] op_sel_hi:[1,0]
	v_pk_mul_f32 v[104:105], v[98:99], v[116:117] op_sel_hi:[1,0]
	v_pk_mul_f32 v[100:101], v[102:103], v[214:215]
	v_pk_mul_f32 v[98:99], v[104:105], v[212:213]
	s_nop 0
	v_cvt_pk_bf16_f32 v222, v98, v99
	v_cvt_pk_bf16_f32 v223, v100, v101
	s_nop 1
	v_permlane16_swap_b32_e32 v220, v222
	v_permlane16_swap_b32_e32 v221, v223
	global_store_dwordx4 v[226:227], v[220:223], off offset:64
.LBB0_519:
	v_mul_f32_e32 v98, v95, v95
	v_fmac_f32_e32 v98, v94, v94
	v_fmac_f32_e32 v98, v96, v96
	v_fmac_f32_e32 v98, v97, v97
	v_fmac_f32_e32 v98, v90, v90
	v_fmac_f32_e32 v98, v91, v91
	v_fmac_f32_e32 v98, v92, v92
	v_fmac_f32_e32 v98, v93, v93
	v_fmac_f32_e32 v98, v86, v86
	v_fmac_f32_e32 v98, v87, v87
	v_fmac_f32_e32 v98, v88, v88
	v_fmac_f32_e32 v98, v89, v89
	v_fmac_f32_e32 v98, v82, v82
	v_fmac_f32_e32 v98, v83, v83
	v_fmac_f32_e32 v98, v84, v84
	v_fmac_f32_e32 v98, v85, v85
	ds_bpermute_b32 v99, v189, v98
	v_or_b32_e32 v104, s47, v180
	s_and_b64 vcc, exec, s[2:3]
	s_mov_b64 s[8:9], -1
	s_waitcnt lgkmcnt(0)
	v_add_f32_e32 v98, v98, v99
	ds_bpermute_b32 v99, v190, v98
	s_waitcnt lgkmcnt(0)
	v_add_f32_e32 v98, v98, v99
	v_fmamk_f32 v98, v98, 0x3c800000, v188
	v_rsq_f32_e32 v102, v98
	s_cbranch_vccnz .LBB0_605
	v_add_u32_e32 v110, 0xffffc000, v104
	v_and_b32_e32 v99, 0x7ef, v104
	v_ashrrev_i32_e32 v98, 3, v110
	v_cndmask_b32_e64 v111, v99, v174, s[6:7]
	v_mov_b32_e32 v99, s38
	v_cndmask_b32_e64 v108, v99, v98, s[6:7]
	s_and_b64 vcc, exec, s[0:1]
	s_cbranch_vccnz .LBB0_535
	s_andn2_b64 vcc, exec, s[60:61]
	s_cbranch_vccnz .LBB0_531
	v_add_u32_e32 v100, 7, v111
	v_mov_b32_e32 v101, v139
	v_ashrrev_i32_e32 v105, 31, v104
	v_mad_i64_i32 v[100:101], s[8:9], v108, 15, v[100:101]
	v_readlane_b32 s10, v253, 43
	v_lshlrev_b64 v[98:99], 11, v[104:105]
	v_lshlrev_b64 v[100:101], 12, v[100:101]
	v_readlane_b32 s11, v253, 44
	v_lshl_add_u64 v[98:99], s[24:25], 0, v[98:99]
	v_cndmask_b32_e64 v103, 0, 1, s[6:7]
	v_lshl_add_u64 v[100:101], s[10:11], 0, v[100:101]
	v_lshl_add_u64 v[98:99], v[138:139], 1, v[98:99]
	v_cvt_pk_bf16_f32 v216, v94, v95
	v_cvt_pk_bf16_f32 v217, v96, v97
	v_cmp_ne_u32_e64 s[8:9], 1, v103
	s_andn2_b64 vcc, exec, s[6:7]
	v_lshl_add_u64 v[100:101], v[138:139], 2, v[100:101]
	s_cbranch_vccnz .LBB0_524
	global_store_dwordx4 v[100:101], v[94:97], off
.LBB0_524:
	v_cvt_pk_bf16_f32 v218, v90, v91
	v_cvt_pk_bf16_f32 v219, v92, v93
	s_and_b64 vcc, exec, s[8:9]
	s_nop 1
	v_permlane16_swap_b32_e32 v216, v218
	v_permlane16_swap_b32_e32 v217, v219
	v_lshl_add_u64 v[226:227], v[224:225], 0, v[98:99]
	global_store_dwordx4 v[226:227], v[216:219], off
	s_cbranch_vccnz .LBB0_526
	global_store_dwordx4 v[100:101], v[90:93], off offset:64
.LBB0_526:
	v_cvt_pk_bf16_f32 v220, v86, v87
	v_cvt_pk_bf16_f32 v221, v88, v89
	s_and_b64 vcc, exec, s[8:9]
	s_cbranch_vccnz .LBB0_528
	global_store_dwordx4 v[100:101], v[86:89], off offset:128
.LBB0_528:
	v_cvt_pk_bf16_f32 v222, v82, v83
	v_cvt_pk_bf16_f32 v223, v84, v85
	s_and_b64 vcc, exec, s[8:9]
	s_nop 1
	v_permlane16_swap_b32_e32 v220, v222
	v_permlane16_swap_b32_e32 v221, v223
	global_store_dwordx4 v[226:227], v[220:223], off offset:64
	s_cbranch_vccnz .LBB0_530
	global_store_dwordx4 v[100:101], v[82:85], off offset:192

.LBB0_605:
	s_andn2_b64 vcc, exec, s[8:9]
	s_cbranch_vccnz .LBB0_607
	v_ashrrev_i32_e32 v105, 31, v104
	v_mul_f32_e32 v100, 0x3e38aa3b, v102
	v_lshlrev_b64 v[98:99], 11, v[104:105]
	v_pk_mul_f32 v[102:103], v[96:97], v[100:101] op_sel_hi:[1,0]
	v_pk_mul_f32 v[104:105], v[94:95], v[100:101] op_sel_hi:[1,0]
	v_lshl_add_u64 v[98:99], s[18:19], 0, v[98:99]
	v_lshl_add_u64 v[98:99], s[62:63], 1, v[98:99]
	v_mov_b32_e32 v131, v139
	v_lshl_add_u64 v[98:99], v[98:99], 0, v[130:131]
	v_pk_mul_f32 v[96:97], v[102:103], v[202:203]
	v_pk_mul_f32 v[94:95], v[104:105], v[200:201]
	s_nop 0
	v_cvt_pk_bf16_f32 v216, v94, v95
	v_cvt_pk_bf16_f32 v217, v96, v97
	v_pk_mul_f32 v[94:95], v[92:93], v[100:101] op_sel_hi:[1,0]
	v_pk_mul_f32 v[96:97], v[90:91], v[100:101] op_sel_hi:[1,0]
	v_pk_mul_f32 v[92:93], v[94:95], v[206:207]
	v_pk_mul_f32 v[90:91], v[96:97], v[204:205]
	s_nop 0
	v_cvt_pk_bf16_f32 v218, v90, v91
	v_cvt_pk_bf16_f32 v219, v92, v93
	s_nop 1
	v_permlane16_swap_b32_e32 v216, v218
	v_permlane16_swap_b32_e32 v217, v219
	v_lshl_add_u64 v[226:227], v[224:225], 0, v[98:99]
	global_store_dwordx4 v[226:227], v[216:219], off
	v_pk_mul_f32 v[90:91], v[88:89], v[100:101] op_sel_hi:[1,0]
	v_pk_mul_f32 v[92:93], v[86:87], v[100:101] op_sel_hi:[1,0]
	v_pk_mul_f32 v[88:89], v[90:91], v[210:211]
	v_pk_mul_f32 v[86:87], v[92:93], v[208:209]
	s_nop 0
	v_cvt_pk_bf16_f32 v220, v86, v87
	v_cvt_pk_bf16_f32 v221, v88, v89
	v_pk_mul_f32 v[86:87], v[84:85], v[100:101] op_sel_hi:[1,0]
	v_pk_mul_f32 v[88:89], v[82:83], v[100:101] op_sel_hi:[1,0]
	v_pk_mul_f32 v[84:85], v[86:87], v[214:215]
	v_pk_mul_f32 v[82:83], v[88:89], v[212:213]
	s_nop 0
	v_cvt_pk_bf16_f32 v222, v82, v83
	v_cvt_pk_bf16_f32 v223, v84, v85
	s_nop 1
	v_permlane16_swap_b32_e32 v220, v222
	v_permlane16_swap_b32_e32 v221, v223
	global_store_dwordx4 v[226:227], v[220:223], off offset:64
.LBB0_607:
	v_mul_f32_e32 v82, v79, v79
	v_fmac_f32_e32 v82, v78, v78
	v_fmac_f32_e32 v82, v80, v80
	v_fmac_f32_e32 v82, v81, v81
	v_fmac_f32_e32 v82, v74, v74
	v_fmac_f32_e32 v82, v75, v75
	v_fmac_f32_e32 v82, v76, v76
	v_fmac_f32_e32 v82, v77, v77
	v_fmac_f32_e32 v82, v70, v70
	v_fmac_f32_e32 v82, v71, v71
	v_fmac_f32_e32 v82, v72, v72
	v_fmac_f32_e32 v82, v73, v73
	v_fmac_f32_e32 v82, v66, v66
	v_fmac_f32_e32 v82, v67, v67
	v_fmac_f32_e32 v82, v68, v68
	v_fmac_f32_e32 v82, v69, v69
	ds_bpermute_b32 v83, v189, v82
	v_or_b32_e32 v88, s47, v181
	s_and_b64 vcc, exec, s[2:3]
	s_mov_b64 s[8:9], -1
	s_waitcnt lgkmcnt(0)
	v_add_f32_e32 v82, v82, v83
	ds_bpermute_b32 v83, v190, v82
	s_waitcnt lgkmcnt(0)
	v_add_f32_e32 v82, v82, v83
	v_fmamk_f32 v82, v82, 0x3c800000, v188
	v_rsq_f32_e32 v86, v82
	s_cbranch_vccnz .LBB0_693
	v_add_u32_e32 v94, 0xffffc000, v88
	v_and_b32_e32 v83, 0x7ff, v88
	v_ashrrev_i32_e32 v82, 3, v94
	v_cndmask_b32_e64 v92, v83, v174, s[6:7]
	v_mov_b32_e32 v83, s38
	v_cndmask_b32_e64 v96, v83, v82, s[6:7]
	s_and_b64 vcc, exec, s[0:1]
	s_cbranch_vccnz .LBB0_623
	s_andn2_b64 vcc, exec, s[60:61]
	s_cbranch_vccnz .LBB0_619
	s_movk_i32 s8, 0x7f0
	v_mov_b32_e32 v93, v139
	v_ashrrev_i32_e32 v89, 31, v88
	v_cmp_lt_u32_e32 vcc, s8, v92
	v_mad_i64_i32 v[84:85], s[8:9], v96, 15, v[92:93]
	v_lshlrev_b64 v[82:83], 11, v[88:89]
	v_lshlrev_b64 v[90:91], 12, v[84:85]
	v_add_u32_e32 v84, 7, v92
	v_mov_b32_e32 v85, v139
	v_mad_i64_i32 v[84:85], s[8:9], v96, 15, v[84:85]
	v_lshl_add_u64 v[82:83], s[24:25], 0, v[82:83]
	v_lshlrev_b64 v[98:99], 12, v[84:85]
	v_lshl_add_u64 v[84:85], v[138:139], 1, v[82:83]
	v_cvt_pk_bf16_f32 v216, v78, v79
	v_cvt_pk_bf16_f32 v217, v80, v81
	s_or_b64 s[8:9], s[6:7], vcc
	v_cndmask_b32_e64 v83, v91, v99, s[6:7]
	v_cndmask_b32_e64 v82, v90, v98, s[6:7]
	s_and_saveexec_b64 s[10:11], s[8:9]
	s_cbranch_execz .LBB0_612
	s_and_b64 s[12:13], s[6:7], exec
	s_mov_b32 s12, 0x15478000
	s_cselect_b32 s12, s12, 0xc80f000
	s_add_u32 s12, s90, s12
	s_addc_u32 s13, s91, 0
	v_lshl_add_u64 v[90:91], s[12:13], 0, v[82:83]
	v_lshl_add_u64 v[90:91], v[138:139], 2, v[90:91]
	global_store_dwordx4 v[90:91], v[78:81], off
.LBB0_612:
	s_or_b64 exec, exec, s[10:11]
	v_cvt_pk_bf16_f32 v218, v74, v75
	v_cvt_pk_bf16_f32 v219, v76, v77
	s_nop 1
	v_permlane16_swap_b32_e32 v216, v218
	v_permlane16_swap_b32_e32 v217, v219
	v_lshl_add_u64 v[226:227], v[224:225], 0, v[84:85]
	global_store_dwordx4 v[226:227], v[216:219], off
	s_and_saveexec_b64 s[10:11], s[8:9]
	s_cbranch_execz .LBB0_614
	s_and_b64 s[12:13], s[6:7], exec
	s_mov_b32 s12, 0x15478000
	s_cselect_b32 s12, s12, 0xc80f000
	s_add_u32 s12, s90, s12
	s_addc_u32 s13, s91, 0
	v_lshl_add_u64 v[90:91], s[12:13], 0, v[82:83]
	v_lshl_add_u64 v[90:91], v[138:139], 2, v[90:91]
	global_store_dwordx4 v[90:91], v[74:77], off offset:64
.LBB0_614:
	s_or_b64 exec, exec, s[10:11]
	v_cvt_pk_bf16_f32 v220, v70, v71
	v_cvt_pk_bf16_f32 v221, v72, v73
	s_and_saveexec_b64 s[10:11], s[8:9]
	s_cbranch_execz .LBB0_616
	s_and_b64 s[12:13], s[6:7], exec
	s_mov_b32 s12, 0x15478000
	s_cselect_b32 s12, s12, 0xc80f000
	s_add_u32 s12, s90, s12
	s_addc_u32 s13, s91, 0
	v_lshl_add_u64 v[90:91], s[12:13], 0, v[82:83]
	v_lshl_add_u64 v[90:91], v[138:139], 2, v[90:91]
	global_store_dwordx4 v[90:91], v[70:73], off offset:128
.LBB0_616:
	s_or_b64 exec, exec, s[10:11]
	v_cvt_pk_bf16_f32 v222, v66, v67
	v_cvt_pk_bf16_f32 v223, v68, v69
	s_nop 1
	v_permlane16_swap_b32_e32 v220, v222
	v_permlane16_swap_b32_e32 v221, v223
	global_store_dwordx4 v[226:227], v[220:223], off offset:64
	s_and_saveexec_b64 s[10:11], s[8:9]
	s_cbranch_execz .LBB0_618
	s_and_b64 s[8:9], s[6:7], exec
	s_mov_b32 s8, 0x15478000
	s_cselect_b32 s8, s8, 0xc80f000
	s_add_u32 s8, s90, s8
	s_addc_u32 s9, s91, 0
	v_lshl_add_u64 v[82:83], s[8:9], 0, v[82:83]
	v_lshl_add_u64 v[82:83], v[138:139], 2, v[82:83]
	global_store_dwordx4 v[82:83], v[66:69], off offset:192

.LBB0_693:
	s_andn2_b64 vcc, exec, s[8:9]
	s_cbranch_vccnz .LBB0_695
	v_ashrrev_i32_e32 v89, 31, v88
	v_mul_f32_e32 v84, 0x3e38aa3b, v86
	v_lshlrev_b64 v[82:83], 11, v[88:89]
	v_pk_mul_f32 v[86:87], v[80:81], v[84:85] op_sel_hi:[1,0]
	v_pk_mul_f32 v[88:89], v[78:79], v[84:85] op_sel_hi:[1,0]
	v_lshl_add_u64 v[82:83], s[18:19], 0, v[82:83]
	v_lshl_add_u64 v[82:83], s[62:63], 1, v[82:83]
	v_mov_b32_e32 v131, v139
	v_lshl_add_u64 v[82:83], v[82:83], 0, v[130:131]
	v_pk_mul_f32 v[80:81], v[86:87], v[202:203]
	v_pk_mul_f32 v[78:79], v[88:89], v[200:201]
	s_nop 0
	v_cvt_pk_bf16_f32 v216, v78, v79
	v_cvt_pk_bf16_f32 v217, v80, v81
	v_pk_mul_f32 v[78:79], v[76:77], v[84:85] op_sel_hi:[1,0]
	v_pk_mul_f32 v[80:81], v[74:75], v[84:85] op_sel_hi:[1,0]
	v_pk_mul_f32 v[76:77], v[78:79], v[206:207]
	v_pk_mul_f32 v[74:75], v[80:81], v[204:205]
	s_nop 0
	v_cvt_pk_bf16_f32 v218, v74, v75
	v_cvt_pk_bf16_f32 v219, v76, v77
	s_nop 1
	v_permlane16_swap_b32_e32 v216, v218
	v_permlane16_swap_b32_e32 v217, v219
	v_lshl_add_u64 v[226:227], v[224:225], 0, v[82:83]
	global_store_dwordx4 v[226:227], v[216:219], off
	v_pk_mul_f32 v[74:75], v[72:73], v[84:85] op_sel_hi:[1,0]
	v_pk_mul_f32 v[76:77], v[70:71], v[84:85] op_sel_hi:[1,0]
	v_pk_mul_f32 v[72:73], v[74:75], v[210:211]
	v_pk_mul_f32 v[70:71], v[76:77], v[208:209]
	s_nop 0
	v_cvt_pk_bf16_f32 v220, v70, v71
	v_cvt_pk_bf16_f32 v221, v72, v73
	v_pk_mul_f32 v[70:71], v[68:69], v[84:85] op_sel_hi:[1,0]
	v_pk_mul_f32 v[72:73], v[66:67], v[84:85] op_sel_hi:[1,0]
	v_pk_mul_f32 v[68:69], v[70:71], v[214:215]
	v_pk_mul_f32 v[66:67], v[72:73], v[212:213]
	s_nop 0
	v_cvt_pk_bf16_f32 v222, v66, v67
	v_cvt_pk_bf16_f32 v223, v68, v69
	s_nop 1
	v_permlane16_swap_b32_e32 v220, v222
	v_permlane16_swap_b32_e32 v221, v223
	global_store_dwordx4 v[226:227], v[220:223], off offset:64
.LBB0_695:
	v_mul_f32_e32 v66, v63, v63
	v_fmac_f32_e32 v66, v62, v62
	v_fmac_f32_e32 v66, v64, v64
	v_fmac_f32_e32 v66, v65, v65
	v_fmac_f32_e32 v66, v58, v58
	v_fmac_f32_e32 v66, v59, v59
	v_fmac_f32_e32 v66, v60, v60
	v_fmac_f32_e32 v66, v61, v61
	v_fmac_f32_e32 v66, v54, v54
	v_fmac_f32_e32 v66, v55, v55
	v_fmac_f32_e32 v66, v56, v56
	v_fmac_f32_e32 v66, v57, v57
	v_fmac_f32_e32 v66, v50, v50
	v_fmac_f32_e32 v66, v51, v51
	v_fmac_f32_e32 v66, v52, v52
	v_fmac_f32_e32 v66, v53, v53
	ds_bpermute_b32 v67, v189, v66
	s_addk_i32 s47, 0x80
	v_or_b32_e32 v70, s47, v1
	s_ashr_i32 s38, s47, 11
	s_and_b64 vcc, exec, s[2:3]
	s_waitcnt lgkmcnt(0)
	v_add_f32_e32 v66, v66, v67
	ds_bpermute_b32 v67, v190, v66
	s_mov_b64 s[8:9], -1
	s_waitcnt lgkmcnt(0)
	v_add_f32_e32 v66, v66, v67
	v_fmamk_f32 v66, v66, 0x3c800000, v188
	v_rsq_f32_e32 v72, v66
	s_cbranch_vccnz .LBB0_781
	v_add_u32_e32 v78, 0xffffc000, v70
	v_and_b32_e32 v67, 0x7cf, v70
	v_ashrrev_i32_e32 v66, 3, v78
	v_cndmask_b32_e64 v79, v67, v174, s[6:7]
	v_mov_b32_e32 v67, s38
	v_cndmask_b32_e64 v76, v67, v66, s[6:7]
	s_and_b64 vcc, exec, s[0:1]
	s_cbranch_vccnz .LBB0_711
	s_andn2_b64 vcc, exec, s[60:61]
	s_cbranch_vccnz .LBB0_707
	v_add_u32_e32 v68, 7, v79
	v_mov_b32_e32 v69, v139
	v_ashrrev_i32_e32 v71, 31, v70
	v_mad_i64_i32 v[68:69], s[8:9], v76, 15, v[68:69]
	v_readlane_b32 s10, v253, 43
	v_lshlrev_b64 v[66:67], 11, v[70:71]
	v_lshlrev_b64 v[68:69], 12, v[68:69]
	v_readlane_b32 s11, v253, 44
	v_lshl_add_u64 v[66:67], s[24:25], 0, v[66:67]
	v_cndmask_b32_e64 v71, 0, 1, s[6:7]
	v_lshl_add_u64 v[68:69], s[10:11], 0, v[68:69]
	v_lshl_add_u64 v[66:67], v[138:139], 1, v[66:67]
	v_cvt_pk_bf16_f32 v216, v62, v63
	v_cvt_pk_bf16_f32 v217, v64, v65
	v_cmp_ne_u32_e64 s[8:9], 1, v71
	s_andn2_b64 vcc, exec, s[6:7]
	v_lshl_add_u64 v[68:69], v[138:139], 2, v[68:69]
	s_cbranch_vccnz .LBB0_700
	global_store_dwordx4 v[68:69], v[62:65], off
.LBB0_700:
	v_cvt_pk_bf16_f32 v218, v58, v59
	v_cvt_pk_bf16_f32 v219, v60, v61
	s_and_b64 vcc, exec, s[8:9]
	s_nop 1
	v_permlane16_swap_b32_e32 v216, v218
	v_permlane16_swap_b32_e32 v217, v219
	v_lshl_add_u64 v[226:227], v[224:225], 0, v[66:67]
	global_store_dwordx4 v[226:227], v[216:219], off
	s_cbranch_vccnz .LBB0_702
	global_store_dwordx4 v[68:69], v[58:61], off offset:64
.LBB0_702:
	v_cvt_pk_bf16_f32 v220, v54, v55
	v_cvt_pk_bf16_f32 v221, v56, v57
	s_and_b64 vcc, exec, s[8:9]
	s_cbranch_vccnz .LBB0_704
	global_store_dwordx4 v[68:69], v[54:57], off offset:128
.LBB0_704:
	v_cvt_pk_bf16_f32 v222, v50, v51
	v_cvt_pk_bf16_f32 v223, v52, v53
	s_and_b64 vcc, exec, s[8:9]
	s_nop 1
	v_permlane16_swap_b32_e32 v220, v222
	v_permlane16_swap_b32_e32 v221, v223
	global_store_dwordx4 v[226:227], v[220:223], off offset:64
	s_cbranch_vccnz .LBB0_706
	global_store_dwordx4 v[68:69], v[50:53], off offset:192

.LBB0_781:
	s_andn2_b64 vcc, exec, s[8:9]
	s_cbranch_vccnz .LBB0_783
	v_ashrrev_i32_e32 v71, 31, v70
	v_mul_f32_e32 v68, 0x3e38aa3b, v72
	v_lshlrev_b64 v[66:67], 11, v[70:71]
	v_pk_mul_f32 v[70:71], v[64:65], v[68:69] op_sel_hi:[1,0]
	v_pk_mul_f32 v[72:73], v[62:63], v[68:69] op_sel_hi:[1,0]
	v_lshl_add_u64 v[66:67], s[18:19], 0, v[66:67]
	v_lshl_add_u64 v[66:67], s[62:63], 1, v[66:67]
	v_mov_b32_e32 v131, v139
	v_lshl_add_u64 v[66:67], v[66:67], 0, v[130:131]
	v_pk_mul_f32 v[64:65], v[70:71], v[202:203]
	v_pk_mul_f32 v[62:63], v[72:73], v[200:201]
	s_nop 0
	v_cvt_pk_bf16_f32 v216, v62, v63
	v_cvt_pk_bf16_f32 v217, v64, v65
	v_pk_mul_f32 v[62:63], v[60:61], v[68:69] op_sel_hi:[1,0]
	v_pk_mul_f32 v[64:65], v[58:59], v[68:69] op_sel_hi:[1,0]
	v_pk_mul_f32 v[60:61], v[62:63], v[206:207]
	v_pk_mul_f32 v[58:59], v[64:65], v[204:205]
	s_nop 0
	v_cvt_pk_bf16_f32 v218, v58, v59
	v_cvt_pk_bf16_f32 v219, v60, v61
	s_nop 1
	v_permlane16_swap_b32_e32 v216, v218
	v_permlane16_swap_b32_e32 v217, v219
	v_lshl_add_u64 v[226:227], v[224:225], 0, v[66:67]
	global_store_dwordx4 v[226:227], v[216:219], off
	v_pk_mul_f32 v[58:59], v[56:57], v[68:69] op_sel_hi:[1,0]
	v_pk_mul_f32 v[60:61], v[54:55], v[68:69] op_sel_hi:[1,0]
	v_pk_mul_f32 v[56:57], v[58:59], v[210:211]
	v_pk_mul_f32 v[54:55], v[60:61], v[208:209]
	s_nop 0
	v_cvt_pk_bf16_f32 v220, v54, v55
	v_cvt_pk_bf16_f32 v221, v56, v57
	v_pk_mul_f32 v[54:55], v[52:53], v[68:69] op_sel_hi:[1,0]
	v_pk_mul_f32 v[56:57], v[50:51], v[68:69] op_sel_hi:[1,0]
	v_pk_mul_f32 v[52:53], v[54:55], v[214:215]
	v_pk_mul_f32 v[50:51], v[56:57], v[212:213]
	s_nop 0
	v_cvt_pk_bf16_f32 v222, v50, v51
	v_cvt_pk_bf16_f32 v223, v52, v53
	s_nop 1
	v_permlane16_swap_b32_e32 v220, v222
	v_permlane16_swap_b32_e32 v221, v223
	global_store_dwordx4 v[226:227], v[220:223], off offset:64
.LBB0_783:
	v_mul_f32_e32 v50, v47, v47
	v_fmac_f32_e32 v50, v46, v46
	v_fmac_f32_e32 v50, v48, v48
	v_fmac_f32_e32 v50, v49, v49
	v_fmac_f32_e32 v50, v42, v42
	v_fmac_f32_e32 v50, v43, v43
	v_fmac_f32_e32 v50, v44, v44
	v_fmac_f32_e32 v50, v45, v45
	v_fmac_f32_e32 v50, v38, v38
	v_fmac_f32_e32 v50, v39, v39
	v_fmac_f32_e32 v50, v40, v40
	v_fmac_f32_e32 v50, v41, v41
	v_fmac_f32_e32 v50, v34, v34
	v_fmac_f32_e32 v50, v35, v35
	v_fmac_f32_e32 v50, v36, v36
	v_fmac_f32_e32 v50, v37, v37
	ds_bpermute_b32 v51, v189, v50
	v_or_b32_e32 v56, s47, v179
	s_and_b64 vcc, exec, s[2:3]
	s_mov_b64 s[8:9], -1
	s_waitcnt lgkmcnt(0)
	v_add_f32_e32 v50, v50, v51
	ds_bpermute_b32 v51, v190, v50
	s_waitcnt lgkmcnt(0)
	v_add_f32_e32 v50, v50, v51
	v_fmamk_f32 v50, v50, 0x3c800000, v188
	v_rsq_f32_e32 v54, v50
	s_cbranch_vccnz .LBB0_869
	v_add_u32_e32 v62, 0xffffc000, v56
	v_and_b32_e32 v51, 0x7df, v56
	v_ashrrev_i32_e32 v50, 3, v62
	v_cndmask_b32_e64 v63, v51, v174, s[6:7]
	v_mov_b32_e32 v51, s38
	v_cndmask_b32_e64 v60, v51, v50, s[6:7]
	s_and_b64 vcc, exec, s[0:1]
	s_cbranch_vccnz .LBB0_799
	s_andn2_b64 vcc, exec, s[60:61]
	s_cbranch_vccnz .LBB0_795
	v_add_u32_e32 v52, 7, v63
	v_mov_b32_e32 v53, v139
	v_ashrrev_i32_e32 v57, 31, v56
	v_mad_i64_i32 v[52:53], s[8:9], v60, 15, v[52:53]
	v_readlane_b32 s10, v253, 43
	v_lshlrev_b64 v[50:51], 11, v[56:57]
	v_lshlrev_b64 v[52:53], 12, v[52:53]
	v_readlane_b32 s11, v253, 44
	v_lshl_add_u64 v[50:51], s[24:25], 0, v[50:51]
	v_cndmask_b32_e64 v55, 0, 1, s[6:7]
	v_lshl_add_u64 v[52:53], s[10:11], 0, v[52:53]
	v_lshl_add_u64 v[50:51], v[138:139], 1, v[50:51]
	v_cvt_pk_bf16_f32 v216, v46, v47
	v_cvt_pk_bf16_f32 v217, v48, v49
	v_cmp_ne_u32_e64 s[8:9], 1, v55
	s_andn2_b64 vcc, exec, s[6:7]
	v_lshl_add_u64 v[52:53], v[138:139], 2, v[52:53]
	s_cbranch_vccnz .LBB0_788
	global_store_dwordx4 v[52:53], v[46:49], off
.LBB0_788:
	v_cvt_pk_bf16_f32 v218, v42, v43
	v_cvt_pk_bf16_f32 v219, v44, v45
	s_and_b64 vcc, exec, s[8:9]
	s_nop 1
	v_permlane16_swap_b32_e32 v216, v218
	v_permlane16_swap_b32_e32 v217, v219
	v_lshl_add_u64 v[226:227], v[224:225], 0, v[50:51]
	global_store_dwordx4 v[226:227], v[216:219], off
	s_cbranch_vccnz .LBB0_790
	global_store_dwordx4 v[52:53], v[42:45], off offset:64
.LBB0_790:
	v_cvt_pk_bf16_f32 v220, v38, v39
	v_cvt_pk_bf16_f32 v221, v40, v41
	s_and_b64 vcc, exec, s[8:9]
	s_cbranch_vccnz .LBB0_792
	global_store_dwordx4 v[52:53], v[38:41], off offset:128
.LBB0_792:
	v_cvt_pk_bf16_f32 v222, v34, v35
	v_cvt_pk_bf16_f32 v223, v36, v37
	s_and_b64 vcc, exec, s[8:9]
	s_nop 1
	v_permlane16_swap_b32_e32 v220, v222
	v_permlane16_swap_b32_e32 v221, v223
	global_store_dwordx4 v[226:227], v[220:223], off offset:64
	s_cbranch_vccnz .LBB0_794
	global_store_dwordx4 v[52:53], v[34:37], off offset:192

.LBB0_869:
	s_andn2_b64 vcc, exec, s[8:9]
	s_cbranch_vccnz .LBB0_871
	v_ashrrev_i32_e32 v57, 31, v56
	v_mul_f32_e32 v52, 0x3e38aa3b, v54
	v_lshlrev_b64 v[50:51], 11, v[56:57]
	v_pk_mul_f32 v[54:55], v[48:49], v[52:53] op_sel_hi:[1,0]
	v_pk_mul_f32 v[56:57], v[46:47], v[52:53] op_sel_hi:[1,0]
	v_lshl_add_u64 v[50:51], s[18:19], 0, v[50:51]
	v_lshl_add_u64 v[50:51], s[62:63], 1, v[50:51]
	v_mov_b32_e32 v131, v139
	v_lshl_add_u64 v[50:51], v[50:51], 0, v[130:131]
	v_pk_mul_f32 v[48:49], v[54:55], v[202:203]
	v_pk_mul_f32 v[46:47], v[56:57], v[200:201]
	s_nop 0
	v_cvt_pk_bf16_f32 v216, v46, v47
	v_cvt_pk_bf16_f32 v217, v48, v49
	v_pk_mul_f32 v[46:47], v[44:45], v[52:53] op_sel_hi:[1,0]
	v_pk_mul_f32 v[48:49], v[42:43], v[52:53] op_sel_hi:[1,0]
	v_pk_mul_f32 v[44:45], v[46:47], v[206:207]
	v_pk_mul_f32 v[42:43], v[48:49], v[204:205]
	s_nop 0
	v_cvt_pk_bf16_f32 v218, v42, v43
	v_cvt_pk_bf16_f32 v219, v44, v45
	s_nop 1
	v_permlane16_swap_b32_e32 v216, v218
	v_permlane16_swap_b32_e32 v217, v219
	v_lshl_add_u64 v[226:227], v[224:225], 0, v[50:51]
	global_store_dwordx4 v[226:227], v[216:219], off
	v_pk_mul_f32 v[42:43], v[40:41], v[52:53] op_sel_hi:[1,0]
	v_pk_mul_f32 v[44:45], v[38:39], v[52:53] op_sel_hi:[1,0]
	v_pk_mul_f32 v[40:41], v[42:43], v[210:211]
	v_pk_mul_f32 v[38:39], v[44:45], v[208:209]
	s_nop 0
	v_cvt_pk_bf16_f32 v220, v38, v39
	v_cvt_pk_bf16_f32 v221, v40, v41
	v_pk_mul_f32 v[38:39], v[36:37], v[52:53] op_sel_hi:[1,0]
	v_pk_mul_f32 v[40:41], v[34:35], v[52:53] op_sel_hi:[1,0]
	v_pk_mul_f32 v[36:37], v[38:39], v[214:215]
	v_pk_mul_f32 v[34:35], v[40:41], v[212:213]
	s_nop 0
	v_cvt_pk_bf16_f32 v222, v34, v35
	v_cvt_pk_bf16_f32 v223, v36, v37
	s_nop 1
	v_permlane16_swap_b32_e32 v220, v222
	v_permlane16_swap_b32_e32 v221, v223
	global_store_dwordx4 v[226:227], v[220:223], off offset:64
.LBB0_871:
	v_mul_f32_e32 v34, v31, v31
	v_fmac_f32_e32 v34, v30, v30
	v_fmac_f32_e32 v34, v32, v32
	v_fmac_f32_e32 v34, v33, v33
	v_fmac_f32_e32 v34, v26, v26
	v_fmac_f32_e32 v34, v27, v27
	v_fmac_f32_e32 v34, v28, v28
	v_fmac_f32_e32 v34, v29, v29
	v_fmac_f32_e32 v34, v22, v22
	v_fmac_f32_e32 v34, v23, v23
	v_fmac_f32_e32 v34, v24, v24
	v_fmac_f32_e32 v34, v25, v25
	v_fmac_f32_e32 v34, v18, v18
	v_fmac_f32_e32 v34, v19, v19
	v_fmac_f32_e32 v34, v20, v20
	v_fmac_f32_e32 v34, v21, v21
	ds_bpermute_b32 v35, v189, v34
	v_or_b32_e32 v40, s47, v180
	s_and_b64 vcc, exec, s[2:3]
	s_mov_b64 s[8:9], -1
	s_waitcnt lgkmcnt(0)
	v_add_f32_e32 v34, v34, v35
	ds_bpermute_b32 v35, v190, v34
	s_waitcnt lgkmcnt(0)
	v_add_f32_e32 v34, v34, v35
	v_fmamk_f32 v34, v34, 0x3c800000, v188
	v_rsq_f32_e32 v38, v34
	s_cbranch_vccnz .LBB0_957
	v_add_u32_e32 v46, 0xffffc000, v40
	v_and_b32_e32 v35, 0x7ef, v40
	v_ashrrev_i32_e32 v34, 3, v46
	v_cndmask_b32_e64 v47, v35, v174, s[6:7]
	v_mov_b32_e32 v35, s38
	v_cndmask_b32_e64 v44, v35, v34, s[6:7]
	s_and_b64 vcc, exec, s[0:1]
	s_cbranch_vccnz .LBB0_887
	s_andn2_b64 vcc, exec, s[60:61]
	s_cbranch_vccnz .LBB0_883
	v_add_u32_e32 v36, 7, v47
	v_mov_b32_e32 v37, v139
	v_ashrrev_i32_e32 v41, 31, v40
	v_mad_i64_i32 v[36:37], s[8:9], v44, 15, v[36:37]
	v_readlane_b32 s10, v253, 43
	v_lshlrev_b64 v[34:35], 11, v[40:41]
	v_lshlrev_b64 v[36:37], 12, v[36:37]
	v_readlane_b32 s11, v253, 44
	v_lshl_add_u64 v[34:35], s[24:25], 0, v[34:35]
	v_cndmask_b32_e64 v39, 0, 1, s[6:7]
	v_lshl_add_u64 v[36:37], s[10:11], 0, v[36:37]
	v_lshl_add_u64 v[34:35], v[138:139], 1, v[34:35]
	v_cvt_pk_bf16_f32 v216, v30, v31
	v_cvt_pk_bf16_f32 v217, v32, v33
	v_cmp_ne_u32_e64 s[8:9], 1, v39
	s_andn2_b64 vcc, exec, s[6:7]
	v_lshl_add_u64 v[36:37], v[138:139], 2, v[36:37]
	s_cbranch_vccnz .LBB0_876
	global_store_dwordx4 v[36:37], v[30:33], off
.LBB0_876:
	v_cvt_pk_bf16_f32 v218, v26, v27
	v_cvt_pk_bf16_f32 v219, v28, v29
	s_and_b64 vcc, exec, s[8:9]
	s_nop 1
	v_permlane16_swap_b32_e32 v216, v218
	v_permlane16_swap_b32_e32 v217, v219
	v_lshl_add_u64 v[226:227], v[224:225], 0, v[34:35]
	global_store_dwordx4 v[226:227], v[216:219], off
	s_cbranch_vccnz .LBB0_878
	global_store_dwordx4 v[36:37], v[26:29], off offset:64
.LBB0_878:
	v_cvt_pk_bf16_f32 v220, v22, v23
	v_cvt_pk_bf16_f32 v221, v24, v25
	s_and_b64 vcc, exec, s[8:9]
	s_cbranch_vccnz .LBB0_880
	global_store_dwordx4 v[36:37], v[22:25], off offset:128
.LBB0_880:
	v_cvt_pk_bf16_f32 v222, v18, v19
	v_cvt_pk_bf16_f32 v223, v20, v21
	s_and_b64 vcc, exec, s[8:9]
	s_nop 1
	v_permlane16_swap_b32_e32 v220, v222
	v_permlane16_swap_b32_e32 v221, v223
	global_store_dwordx4 v[226:227], v[220:223], off offset:64
	s_cbranch_vccnz .LBB0_882
	global_store_dwordx4 v[36:37], v[18:21], off offset:192

.LBB0_957:
	s_andn2_b64 vcc, exec, s[8:9]
	s_cbranch_vccnz .LBB0_959
	v_ashrrev_i32_e32 v41, 31, v40
	v_mul_f32_e32 v36, 0x3e38aa3b, v38
	v_lshlrev_b64 v[34:35], 11, v[40:41]
	v_pk_mul_f32 v[38:39], v[32:33], v[36:37] op_sel_hi:[1,0]
	v_pk_mul_f32 v[40:41], v[30:31], v[36:37] op_sel_hi:[1,0]
	v_lshl_add_u64 v[34:35], s[18:19], 0, v[34:35]
	v_lshl_add_u64 v[34:35], s[62:63], 1, v[34:35]
	v_mov_b32_e32 v131, v139
	v_lshl_add_u64 v[34:35], v[34:35], 0, v[130:131]
	v_pk_mul_f32 v[32:33], v[38:39], v[202:203]
	v_pk_mul_f32 v[30:31], v[40:41], v[200:201]
	s_nop 0
	v_cvt_pk_bf16_f32 v216, v30, v31
	v_cvt_pk_bf16_f32 v217, v32, v33
	v_pk_mul_f32 v[30:31], v[28:29], v[36:37] op_sel_hi:[1,0]
	v_pk_mul_f32 v[32:33], v[26:27], v[36:37] op_sel_hi:[1,0]
	v_pk_mul_f32 v[28:29], v[30:31], v[206:207]
	v_pk_mul_f32 v[26:27], v[32:33], v[204:205]
	s_nop 0
	v_cvt_pk_bf16_f32 v218, v26, v27
	v_cvt_pk_bf16_f32 v219, v28, v29
	s_nop 1
	v_permlane16_swap_b32_e32 v216, v218
	v_permlane16_swap_b32_e32 v217, v219
	v_lshl_add_u64 v[226:227], v[224:225], 0, v[34:35]
	global_store_dwordx4 v[226:227], v[216:219], off
	v_pk_mul_f32 v[26:27], v[24:25], v[36:37] op_sel_hi:[1,0]
	v_pk_mul_f32 v[28:29], v[22:23], v[36:37] op_sel_hi:[1,0]
	v_pk_mul_f32 v[24:25], v[26:27], v[210:211]
	v_pk_mul_f32 v[22:23], v[28:29], v[208:209]
	s_nop 0
	v_cvt_pk_bf16_f32 v220, v22, v23
	v_cvt_pk_bf16_f32 v221, v24, v25
	v_pk_mul_f32 v[22:23], v[20:21], v[36:37] op_sel_hi:[1,0]
	v_pk_mul_f32 v[24:25], v[18:19], v[36:37] op_sel_hi:[1,0]
	v_pk_mul_f32 v[20:21], v[22:23], v[214:215]
	v_pk_mul_f32 v[18:19], v[24:25], v[212:213]
	s_nop 0
	v_cvt_pk_bf16_f32 v222, v18, v19
	v_cvt_pk_bf16_f32 v223, v20, v21
	s_nop 1
	v_permlane16_swap_b32_e32 v220, v222
	v_permlane16_swap_b32_e32 v221, v223
	global_store_dwordx4 v[226:227], v[220:223], off offset:64
.LBB0_959:
	v_mul_f32_e32 v18, v15, v15
	v_fmac_f32_e32 v18, v14, v14
	v_fmac_f32_e32 v18, v16, v16
	v_fmac_f32_e32 v18, v17, v17
	v_fmac_f32_e32 v18, v10, v10
	v_fmac_f32_e32 v18, v11, v11
	v_fmac_f32_e32 v18, v12, v12
	v_fmac_f32_e32 v18, v13, v13
	v_fmac_f32_e32 v18, v6, v6
	v_fmac_f32_e32 v18, v7, v7
	v_fmac_f32_e32 v18, v8, v8
	v_fmac_f32_e32 v18, v9, v9
	v_fmac_f32_e32 v18, v2, v2
	v_fmac_f32_e32 v18, v3, v3
	v_fmac_f32_e32 v18, v4, v4
	v_fmac_f32_e32 v18, v5, v5
	ds_bpermute_b32 v19, v189, v18
	v_or_b32_e32 v22, s47, v181
	s_and_b64 vcc, exec, s[2:3]
	s_mov_b64 s[2:3], -1
	s_waitcnt lgkmcnt(0)
	v_add_f32_e32 v18, v18, v19
	ds_bpermute_b32 v19, v190, v18
	s_waitcnt lgkmcnt(0)
	v_add_f32_e32 v18, v18, v19
	v_fmamk_f32 v18, v18, 0x3c800000, v188
	v_rsq_f32_e32 v24, v18
	s_cbranch_vccnz .LBB0_1045
	v_add_u32_e32 v30, 0xffffc000, v22
	v_and_b32_e32 v19, 0x7ff, v22
	v_ashrrev_i32_e32 v18, 3, v30
	v_cndmask_b32_e64 v28, v19, v174, s[6:7]
	v_mov_b32_e32 v19, s38
	v_cndmask_b32_e64 v32, v19, v18, s[6:7]
	s_and_b64 vcc, exec, s[0:1]
	s_mov_b64 s[0:1], -1
	s_cbranch_vccnz .LBB0_975
	s_andn2_b64 vcc, exec, s[60:61]
	s_cbranch_vccnz .LBB0_971
	s_movk_i32 s0, 0x7f0
	v_mov_b32_e32 v29, v139
	v_ashrrev_i32_e32 v23, 31, v22
	v_cmp_lt_u32_e32 vcc, s0, v28
	v_mad_i64_i32 v[20:21], s[0:1], v32, 15, v[28:29]
	v_lshlrev_b64 v[18:19], 11, v[22:23]
	v_lshlrev_b64 v[26:27], 12, v[20:21]
	v_add_u32_e32 v20, 7, v28
	v_mov_b32_e32 v21, v139
	v_mad_i64_i32 v[20:21], s[0:1], v32, 15, v[20:21]
	v_lshl_add_u64 v[18:19], s[24:25], 0, v[18:19]
	v_lshlrev_b64 v[34:35], 12, v[20:21]
	v_lshl_add_u64 v[20:21], v[138:139], 1, v[18:19]
	v_cvt_pk_bf16_f32 v216, v14, v15
	v_cvt_pk_bf16_f32 v217, v16, v17
	s_or_b64 s[0:1], s[6:7], vcc
	v_cndmask_b32_e64 v19, v27, v35, s[6:7]
	v_cndmask_b32_e64 v18, v26, v34, s[6:7]
	s_and_saveexec_b64 s[2:3], s[0:1]
	s_cbranch_execz .LBB0_964
	s_and_b64 s[8:9], s[6:7], exec
	s_mov_b32 s8, 0x15478000
	s_cselect_b32 s8, s8, 0xc80f000
	s_add_u32 s8, s90, s8
	s_addc_u32 s9, s91, 0
	v_lshl_add_u64 v[26:27], s[8:9], 0, v[18:19]
	v_lshl_add_u64 v[26:27], v[138:139], 2, v[26:27]
	global_store_dwordx4 v[26:27], v[14:17], off
.LBB0_964:
	s_or_b64 exec, exec, s[2:3]
	v_cvt_pk_bf16_f32 v218, v10, v11
	v_cvt_pk_bf16_f32 v219, v12, v13
	s_nop 1
	v_permlane16_swap_b32_e32 v216, v218
	v_permlane16_swap_b32_e32 v217, v219
	v_lshl_add_u64 v[226:227], v[224:225], 0, v[20:21]
	global_store_dwordx4 v[226:227], v[216:219], off
	s_and_saveexec_b64 s[2:3], s[0:1]
	s_cbranch_execz .LBB0_966
	s_and_b64 s[8:9], s[6:7], exec
	s_mov_b32 s8, 0x15478000
	s_cselect_b32 s8, s8, 0xc80f000
	s_add_u32 s8, s90, s8
	s_addc_u32 s9, s91, 0
	v_lshl_add_u64 v[26:27], s[8:9], 0, v[18:19]
	v_lshl_add_u64 v[26:27], v[138:139], 2, v[26:27]
	global_store_dwordx4 v[26:27], v[10:13], off offset:64
.LBB0_966:
	s_or_b64 exec, exec, s[2:3]
	v_cvt_pk_bf16_f32 v220, v6, v7
	v_cvt_pk_bf16_f32 v221, v8, v9
	s_and_saveexec_b64 s[2:3], s[0:1]
	s_cbranch_execz .LBB0_968
	s_and_b64 s[8:9], s[6:7], exec
	s_mov_b32 s8, 0x15478000
	s_cselect_b32 s8, s8, 0xc80f000
	s_add_u32 s8, s90, s8
	s_addc_u32 s9, s91, 0
	v_lshl_add_u64 v[26:27], s[8:9], 0, v[18:19]
	v_lshl_add_u64 v[26:27], v[138:139], 2, v[26:27]
	global_store_dwordx4 v[26:27], v[6:9], off offset:128
.LBB0_968:
	s_or_b64 exec, exec, s[2:3]
	v_cvt_pk_bf16_f32 v222, v2, v3
	v_cvt_pk_bf16_f32 v223, v4, v5
	s_nop 1
	v_permlane16_swap_b32_e32 v220, v222
	v_permlane16_swap_b32_e32 v221, v223
	global_store_dwordx4 v[226:227], v[220:223], off offset:64
	s_and_saveexec_b64 s[2:3], s[0:1]
	s_cbranch_execz .LBB0_970
	s_and_b64 s[0:1], s[6:7], exec
	s_mov_b32 s0, 0x15478000
	s_cselect_b32 s0, s0, 0xc80f000
	s_add_u32 s0, s90, s0
	s_addc_u32 s1, s91, 0
	v_lshl_add_u64 v[18:19], s[0:1], 0, v[18:19]
	v_lshl_add_u64 v[18:19], v[138:139], 2, v[18:19]
	global_store_dwordx4 v[18:19], v[2:5], off offset:192

.LBB0_1045:
	s_andn2_b64 vcc, exec, s[2:3]
	s_cbranch_vccnz .LBB0_334
	v_ashrrev_i32_e32 v23, 31, v22
	v_mul_f32_e32 v24, 0x3e38aa3b, v24
	v_lshlrev_b64 v[22:23], 11, v[22:23]
	v_pk_mul_f32 v[16:17], v[16:17], v[24:25] op_sel_hi:[1,0]
	v_pk_mul_f32 v[14:15], v[14:15], v[24:25] op_sel_hi:[1,0]
	v_lshl_add_u64 v[22:23], s[18:19], 0, v[22:23]
	v_mov_b32_e32 v131, v139
	v_lshl_add_u64 v[22:23], s[62:63], 1, v[22:23]
	v_lshl_add_u64 v[22:23], v[22:23], 0, v[130:131]
	v_pk_mul_f32 v[12:13], v[12:13], v[24:25] op_sel_hi:[1,0]
	v_pk_mul_f32 v[10:11], v[10:11], v[24:25] op_sel_hi:[1,0]
	v_pk_mul_f32 v[8:9], v[8:9], v[24:25] op_sel_hi:[1,0]
	v_pk_mul_f32 v[6:7], v[6:7], v[24:25] op_sel_hi:[1,0]
	v_pk_mul_f32 v[4:5], v[4:5], v[24:25] op_sel_hi:[1,0]
	v_pk_mul_f32 v[2:3], v[2:3], v[24:25] op_sel_hi:[1,0]
	v_pk_mul_f32 v[16:17], v[16:17], v[202:203]
	v_pk_mul_f32 v[14:15], v[14:15], v[200:201]
	s_nop 0
	v_cvt_pk_bf16_f32 v216, v14, v15
	v_cvt_pk_bf16_f32 v217, v16, v17
	v_pk_mul_f32 v[12:13], v[12:13], v[206:207]
	v_pk_mul_f32 v[10:11], v[10:11], v[204:205]
	s_nop 0
	v_cvt_pk_bf16_f32 v218, v10, v11
	v_cvt_pk_bf16_f32 v219, v12, v13
	s_nop 1
	v_permlane16_swap_b32_e32 v216, v218
	v_permlane16_swap_b32_e32 v217, v219
	v_lshl_add_u64 v[226:227], v[224:225], 0, v[22:23]
	global_store_dwordx4 v[226:227], v[216:219], off
	v_pk_mul_f32 v[8:9], v[8:9], v[210:211]
	v_pk_mul_f32 v[6:7], v[6:7], v[208:209]
	s_nop 0
	v_cvt_pk_bf16_f32 v220, v6, v7
	v_cvt_pk_bf16_f32 v221, v8, v9
	v_pk_mul_f32 v[4:5], v[4:5], v[214:215]
	v_pk_mul_f32 v[2:3], v[2:3], v[212:213]
	s_nop 0
	v_cvt_pk_bf16_f32 v222, v2, v3
	v_cvt_pk_bf16_f32 v223, v4, v5
	s_nop 1
	v_permlane16_swap_b32_e32 v220, v222
	v_permlane16_swap_b32_e32 v221, v223
	global_store_dwordx4 v[226:227], v[220:223], off offset:64
	s_branch .LBB0_334
